# attnB epilogue: output tile staged through swizzled LDS, 8 row-contiguous dwordx4 stores (4 x 256 B per instruction) per wave
# baseline (speedup 1.0000x reference)
; __device__ __forceinline__ void attnB_unit(const bf16* Q, const bf16* __restrict__ K, const bf16* __restrict__ V, bf16* O, long rowbase, int seq, int h, int q0, float lam, char* lds, LAS unsigned char* lds3) {
;     ...
;     __syncthreads();
;     if (c == 0) {
;         float ss = 0.f;
; #pragma unroll
;         for (int d0 = 0; d0 < 4; ++d0)
; #pragma unroll
;             for (int r = 0; r < 16; ++r) { const float v = o[d0][r] * rl - lam * X[(d0 * 16 + r) * 64]; o[d0][r] = v; ss += v * v; }
.LBB0_304:
	s_cmpk_gt_u32 s28, 0xff
	s_waitcnt lgkmcnt(0)
	s_barrier
	s_cbranch_scc1 .LBB0_265
	ds_read2st64_b32 v[4:5], v1 offset1:1
	ds_read2st64_b32 v[10:11], v1 offset0:2 offset1:3
	ds_read2st64_b32 v[14:15], v1 offset0:4 offset1:5
	ds_read2st64_b32 v[86:87], v1 offset0:14 offset1:15
	v_mov_b32_e32 v2, v66
	s_waitcnt lgkmcnt(3)
	v_mov_b32_e32 v3, v4
	v_mul_f32_e32 v4, v163, v4
	v_pk_fma_f32 v[2:3], v[162:163], v[2:3], v[4:5] op_sel_hi:[1,1,0] neg_lo:[0,0,1] neg_hi:[0,0,1]
	v_mov_b32_e32 v4, v67
	v_mul_f32_e32 v6, v163, v5
	v_pk_fma_f32 v[4:5], v[162:163], v[4:5], v[6:7] op_sel_hi:[1,1,0] neg_lo:[0,0,1] neg_hi:[0,0,1]
	ds_read2st64_b32 v[88:89], v1 offset0:16 offset1:17
	ds_read2st64_b32 v[96:97], v1 offset0:24 offset1:25
	ds_read2st64_b32 v[104:105], v1 offset0:32 offset1:33
	v_pk_mul_f32 v[6:7], v[4:5], v[4:5]
	ds_read2st64_b32 v[112:113], v1 offset0:40 offset1:41
	ds_read2st64_b32 v[114:115], v1 offset0:42 offset1:43
	ds_read2st64_b32 v[116:117], v1 offset0:44 offset1:45
	ds_read2st64_b32 v[118:119], v1 offset0:46 offset1:47
	v_pk_fma_f32 v[8:9], v[2:3], v[2:3], v[6:7]
	v_mov_b32_e32 v6, v68
	s_waitcnt lgkmcnt(9)
	v_mov_b32_e32 v7, v10
	v_mul_f32_e32 v10, v163, v10
	v_pk_fma_f32 v[6:7], v[162:163], v[6:7], v[10:11] op_sel_hi:[1,1,0] neg_lo:[0,0,1] neg_hi:[0,0,1]
	v_mov_b32_e32 v10, v69
	ds_read2st64_b32 v[68:69], v1 offset0:6 offset1:7
	v_pk_fma_f32 v[12:13], v[6:7], v[6:7], v[8:9]
	v_mul_f32_e32 v8, v163, v11
	v_pk_fma_f32 v[8:9], v[162:163], v[10:11], v[8:9] op_sel_hi:[1,1,0] neg_lo:[0,0,1] neg_hi:[0,0,1]
	v_mov_b32_e32 v10, v70
	s_waitcnt lgkmcnt(9)
	v_mov_b32_e32 v11, v14
	v_mul_f32_e32 v14, v163, v14
	v_pk_fma_f32 v[12:13], v[8:9], v[8:9], v[12:13]
	v_pk_fma_f32 v[10:11], v[162:163], v[10:11], v[14:15] op_sel_hi:[1,1,0] neg_lo:[0,0,1] neg_hi:[0,0,1]
	v_mov_b32_e32 v14, v71
	v_pk_fma_f32 v[66:67], v[10:11], v[10:11], v[12:13]
	v_mul_f32_e32 v12, v163, v15
	v_pk_fma_f32 v[12:13], v[162:163], v[14:15], v[12:13] op_sel_hi:[1,1,0] neg_lo:[0,0,1] neg_hi:[0,0,1]
	v_mov_b32_e32 v14, v72
	s_waitcnt lgkmcnt(0)
	v_mov_b32_e32 v15, v68
	v_mul_f32_e32 v68, v163, v68
	v_pk_fma_f32 v[14:15], v[162:163], v[14:15], v[68:69] op_sel_hi:[1,1,0] neg_lo:[0,0,1] neg_hi:[0,0,1]
	v_mov_b32_e32 v68, v73
	ds_read2st64_b32 v[72:73], v1 offset0:8 offset1:9
	ds_read2st64_b32 v[90:91], v1 offset0:18 offset1:19
	ds_read2st64_b32 v[98:99], v1 offset0:26 offset1:27
	ds_read2st64_b32 v[106:107], v1 offset0:34 offset1:35
	v_pk_fma_f32 v[66:67], v[12:13], v[12:13], v[66:67]
	ds_read2st64_b32 v[92:93], v1 offset0:20 offset1:21
	ds_read2st64_b32 v[100:101], v1 offset0:28 offset1:29
	ds_read2st64_b32 v[108:109], v1 offset0:36 offset1:37
	v_pk_fma_f32 v[70:71], v[14:15], v[14:15], v[66:67]
	v_mul_f32_e32 v66, v163, v69
	v_pk_fma_f32 v[66:67], v[162:163], v[68:69], v[66:67] op_sel_hi:[1,1,0] neg_lo:[0,0,1] neg_hi:[0,0,1]
	v_mov_b32_e32 v68, v74
	s_waitcnt lgkmcnt(6)
	v_mov_b32_e32 v69, v72
	v_mul_f32_e32 v72, v163, v72
	v_pk_fma_f32 v[70:71], v[66:67], v[66:67], v[70:71]
	v_pk_fma_f32 v[68:69], v[162:163], v[68:69], v[72:73] op_sel_hi:[1,1,0] neg_lo:[0,0,1] neg_hi:[0,0,1]
	v_mov_b32_e32 v72, v75
	v_pk_fma_f32 v[82:83], v[68:69], v[68:69], v[70:71]
	v_mul_f32_e32 v70, v163, v73
	v_pk_fma_f32 v[70:71], v[162:163], v[72:73], v[70:71] op_sel_hi:[1,1,0] neg_lo:[0,0,1] neg_hi:[0,0,1]
	v_mov_b32_e32 v72, v76
	v_pk_fma_f32 v[74:75], v[70:71], v[70:71], v[82:83]
	ds_read2st64_b32 v[82:83], v1 offset0:10 offset1:11
	ds_read2st64_b32 v[94:95], v1 offset0:22 offset1:23
	ds_read2st64_b32 v[102:103], v1 offset0:30 offset1:31
	ds_read2st64_b32 v[110:111], v1 offset0:38 offset1:39
	ds_read2st64_b32 v[120:121], v1 offset0:48 offset1:49
	ds_read2st64_b32 v[122:123], v1 offset0:50 offset1:51
	ds_read2st64_b32 v[124:125], v1 offset0:52 offset1:53
	ds_read2st64_b32 v[126:127], v1 offset0:54 offset1:55
	s_waitcnt lgkmcnt(7)
	v_mov_b32_e32 v73, v82
	v_mul_f32_e32 v76, v163, v82
	v_pk_fma_f32 v[72:73], v[162:163], v[72:73], v[76:77] op_sel_hi:[1,1,0] neg_lo:[0,0,1] neg_hi:[0,0,1]
	v_mov_b32_e32 v82, v77
	v_pk_fma_f32 v[84:85], v[72:73], v[72:73], v[74:75]
	v_mul_f32_e32 v74, v163, v83
	v_pk_fma_f32 v[74:75], v[162:163], v[82:83], v[74:75] op_sel_hi:[1,1,0] neg_lo:[0,0,1] neg_hi:[0,0,1]
	v_mov_b32_e32 v76, v78
	v_pk_fma_f32 v[82:83], v[74:75], v[74:75], v[84:85]
	ds_read2st64_b32 v[84:85], v1 offset0:12 offset1:13
	ds_read2st64_b32 v[128:129], v1 offset0:56 offset1:57
	ds_read2st64_b32 v[130:131], v1 offset0:58 offset1:59
	ds_read2st64_b32 v[132:133], v1 offset0:60 offset1:61
	s_waitcnt lgkmcnt(3)
; __device__ __forceinline__ void attnB_unit(const bf16* Q, const bf16* __restrict__ K, const bf16* __restrict__ V, bf16* O, long rowbase, int seq, int h, int q0, float lam, char* lds, LAS unsigned char* lds3) {
;     ...
;         for (int d0 = 0; d0 < 4; ++d0)
; #pragma unroll
;             for (int r = 0; r < 16; ++r) { const float v = o[d0][r] * rl - lam * X[(d0 * 16 + r) * 64]; o[d0][r] = v; ss += v * v; }
	v_mov_b32_e32 v77, v84
	v_mul_f32_e32 v78, v163, v84
	v_pk_fma_f32 v[76:77], v[162:163], v[76:77], v[78:79] op_sel_hi:[1,1,0] neg_lo:[0,0,1] neg_hi:[0,0,1]
	v_mov_b32_e32 v84, v79
	v_mul_f32_e32 v78, v163, v85
	v_pk_fma_f32 v[82:83], v[76:77], v[76:77], v[82:83]
	v_pk_fma_f32 v[78:79], v[162:163], v[84:85], v[78:79] op_sel_hi:[1,1,0] neg_lo:[0,0,1] neg_hi:[0,0,1]
	s_nop 0
	v_pk_fma_f32 v[84:85], v[78:79], v[78:79], v[82:83]
	v_mov_b32_e32 v82, v80
	v_mov_b32_e32 v83, v86
	v_mul_f32_e32 v80, v163, v86
	v_pk_fma_f32 v[82:83], v[162:163], v[82:83], v[80:81] op_sel_hi:[1,1,0] neg_lo:[0,0,1] neg_hi:[0,0,1]
	v_mov_b32_e32 v86, v81
	v_mul_f32_e32 v80, v163, v87
	v_pk_fma_f32 v[84:85], v[82:83], v[82:83], v[84:85]
	v_pk_fma_f32 v[80:81], v[162:163], v[86:87], v[80:81] op_sel_hi:[1,1,0] neg_lo:[0,0,1] neg_hi:[0,0,1]
	s_nop 0
	v_pk_fma_f32 v[86:87], v[80:81], v[80:81], v[84:85]
	v_mov_b32_e32 v84, v50
	v_mov_b32_e32 v85, v88
	v_mul_f32_e32 v50, v163, v88
	v_pk_fma_f32 v[84:85], v[162:163], v[84:85], v[50:51] op_sel_hi:[1,1,0] neg_lo:[0,0,1] neg_hi:[0,0,1]
	v_mov_b32_e32 v88, v51
	v_mul_f32_e32 v50, v163, v89
	v_pk_fma_f32 v[86:87], v[84:85], v[84:85], v[86:87]
	v_pk_fma_f32 v[50:51], v[162:163], v[88:89], v[50:51] op_sel_hi:[1,1,0] neg_lo:[0,0,1] neg_hi:[0,0,1]
	s_nop 0
	v_pk_fma_f32 v[88:89], v[50:51], v[50:51], v[86:87]
	v_mov_b32_e32 v86, v52
	v_mov_b32_e32 v87, v90
	v_mul_f32_e32 v52, v163, v90
	v_pk_fma_f32 v[86:87], v[162:163], v[86:87], v[52:53] op_sel_hi:[1,1,0] neg_lo:[0,0,1] neg_hi:[0,0,1]
	v_mov_b32_e32 v90, v53
	v_mul_f32_e32 v52, v163, v91
	v_pk_fma_f32 v[88:89], v[86:87], v[86:87], v[88:89]
	v_pk_fma_f32 v[52:53], v[162:163], v[90:91], v[52:53] op_sel_hi:[1,1,0] neg_lo:[0,0,1] neg_hi:[0,0,1]
	s_nop 0
	v_pk_fma_f32 v[90:91], v[52:53], v[52:53], v[88:89]
	v_mov_b32_e32 v88, v54
	v_mov_b32_e32 v89, v92
	v_mul_f32_e32 v54, v163, v92
	v_pk_fma_f32 v[88:89], v[162:163], v[88:89], v[54:55] op_sel_hi:[1,1,0] neg_lo:[0,0,1] neg_hi:[0,0,1]
	v_mov_b32_e32 v92, v55
	v_mul_f32_e32 v54, v163, v93
	v_pk_fma_f32 v[90:91], v[88:89], v[88:89], v[90:91]
	v_pk_fma_f32 v[54:55], v[162:163], v[92:93], v[54:55] op_sel_hi:[1,1,0] neg_lo:[0,0,1] neg_hi:[0,0,1]
	s_nop 0
	v_pk_fma_f32 v[92:93], v[54:55], v[54:55], v[90:91]
	v_mov_b32_e32 v90, v56
	v_mov_b32_e32 v91, v94
	v_mul_f32_e32 v56, v163, v94
	v_pk_fma_f32 v[90:91], v[162:163], v[90:91], v[56:57] op_sel_hi:[1,1,0] neg_lo:[0,0,1] neg_hi:[0,0,1]
	v_mov_b32_e32 v94, v57
	v_mul_f32_e32 v56, v163, v95
	v_pk_fma_f32 v[92:93], v[90:91], v[90:91], v[92:93]
	v_pk_fma_f32 v[56:57], v[162:163], v[94:95], v[56:57] op_sel_hi:[1,1,0] neg_lo:[0,0,1] neg_hi:[0,0,1]
	s_nop 0
	v_pk_fma_f32 v[94:95], v[56:57], v[56:57], v[92:93]
	v_mov_b32_e32 v92, v58
	v_mov_b32_e32 v93, v96
	v_mul_f32_e32 v58, v163, v96
	v_pk_fma_f32 v[92:93], v[162:163], v[92:93], v[58:59] op_sel_hi:[1,1,0] neg_lo:[0,0,1] neg_hi:[0,0,1]
	v_mov_b32_e32 v96, v59
	v_mul_f32_e32 v58, v163, v97
	v_pk_fma_f32 v[94:95], v[92:93], v[92:93], v[94:95]
	v_pk_fma_f32 v[58:59], v[162:163], v[96:97], v[58:59] op_sel_hi:[1,1,0] neg_lo:[0,0,1] neg_hi:[0,0,1]
	s_nop 0
	v_pk_fma_f32 v[96:97], v[58:59], v[58:59], v[94:95]
	v_mov_b32_e32 v94, v60
	v_mov_b32_e32 v95, v98
	v_mul_f32_e32 v60, v163, v98
	v_pk_fma_f32 v[94:95], v[162:163], v[94:95], v[60:61] op_sel_hi:[1,1,0] neg_lo:[0,0,1] neg_hi:[0,0,1]
	v_mov_b32_e32 v98, v61
	v_mul_f32_e32 v60, v163, v99
	v_pk_fma_f32 v[96:97], v[94:95], v[94:95], v[96:97]
	v_pk_fma_f32 v[60:61], v[162:163], v[98:99], v[60:61] op_sel_hi:[1,1,0] neg_lo:[0,0,1] neg_hi:[0,0,1]
	s_nop 0
	v_pk_fma_f32 v[98:99], v[60:61], v[60:61], v[96:97]
	v_mov_b32_e32 v96, v62
	v_mov_b32_e32 v97, v100
	v_mul_f32_e32 v62, v163, v100
	v_pk_fma_f32 v[96:97], v[162:163], v[96:97], v[62:63] op_sel_hi:[1,1,0] neg_lo:[0,0,1] neg_hi:[0,0,1]
	v_mov_b32_e32 v100, v63
	v_mul_f32_e32 v62, v163, v101
	v_pk_fma_f32 v[98:99], v[96:97], v[96:97], v[98:99]
	v_pk_fma_f32 v[62:63], v[162:163], v[100:101], v[62:63] op_sel_hi:[1,1,0] neg_lo:[0,0,1] neg_hi:[0,0,1]
	s_nop 0
	v_pk_fma_f32 v[100:101], v[62:63], v[62:63], v[98:99]
	v_mov_b32_e32 v98, v64
	v_mov_b32_e32 v99, v102
	v_mul_f32_e32 v64, v163, v102
	v_pk_fma_f32 v[98:99], v[162:163], v[98:99], v[64:65] op_sel_hi:[1,1,0] neg_lo:[0,0,1] neg_hi:[0,0,1]
	v_mov_b32_e32 v102, v65
	v_mul_f32_e32 v64, v163, v103
	v_pk_fma_f32 v[100:101], v[98:99], v[98:99], v[100:101]
	v_pk_fma_f32 v[64:65], v[162:163], v[102:103], v[64:65] op_sel_hi:[1,1,0] neg_lo:[0,0,1] neg_hi:[0,0,1]
	s_nop 0
	v_pk_fma_f32 v[102:103], v[64:65], v[64:65], v[100:101]
	v_mov_b32_e32 v100, v34
	v_mov_b32_e32 v101, v104
	v_mul_f32_e32 v34, v163, v104
	v_pk_fma_f32 v[100:101], v[162:163], v[100:101], v[34:35] op_sel_hi:[1,1,0] neg_lo:[0,0,1] neg_hi:[0,0,1]
	v_mov_b32_e32 v104, v35
	v_mul_f32_e32 v34, v163, v105
	v_pk_fma_f32 v[102:103], v[100:101], v[100:101], v[102:103]
	v_pk_fma_f32 v[34:35], v[162:163], v[104:105], v[34:35] op_sel_hi:[1,1,0] neg_lo:[0,0,1] neg_hi:[0,0,1]
	s_nop 0
	v_pk_fma_f32 v[104:105], v[34:35], v[34:35], v[102:103]
	v_mov_b32_e32 v102, v36
	v_mov_b32_e32 v103, v106
	v_mul_f32_e32 v36, v163, v106
	v_pk_fma_f32 v[102:103], v[162:163], v[102:103], v[36:37] op_sel_hi:[1,1,0] neg_lo:[0,0,1] neg_hi:[0,0,1]
	v_mov_b32_e32 v106, v37
	v_mul_f32_e32 v36, v163, v107
	v_pk_fma_f32 v[104:105], v[102:103], v[102:103], v[104:105]
	v_pk_fma_f32 v[36:37], v[162:163], v[106:107], v[36:37] op_sel_hi:[1,1,0] neg_lo:[0,0,1] neg_hi:[0,0,1]
	s_nop 0
	v_pk_fma_f32 v[106:107], v[36:37], v[36:37], v[104:105]
	v_mov_b32_e32 v104, v38
	v_mov_b32_e32 v105, v108
	v_mul_f32_e32 v38, v163, v108
	v_pk_fma_f32 v[104:105], v[162:163], v[104:105], v[38:39] op_sel_hi:[1,1,0] neg_lo:[0,0,1] neg_hi:[0,0,1]
; __device__ __forceinline__ void attnB_unit(const bf16* Q, const bf16* __restrict__ K, const bf16* __restrict__ V, bf16* O, long rowbase, int seq, int h, int q0, float lam, char* lds, LAS unsigned char* lds3) {
;     ...
;     if (c == 0) {
;         float ss = 0.f;
; #pragma unroll
;         for (int d0 = 0; d0 < 4; ++d0)
; #pragma unroll
;             for (int r = 0; r < 16; ++r) { const float v = o[d0][r] * rl - lam * X[(d0 * 16 + r) * 64]; o[d0][r] = v; ss += v * v; }
;         { auto rr = __builtin_amdgcn_permlane32_swap(__float_as_uint(ss), __float_as_uint(ss), false, false); ss = __uint_as_float(rr[0]) + __uint_as_float(rr[1]); }
	v_mov_b32_e32 v108, v39
	v_mul_f32_e32 v38, v163, v109
	v_pk_fma_f32 v[106:107], v[104:105], v[104:105], v[106:107]
	v_pk_fma_f32 v[38:39], v[162:163], v[108:109], v[38:39] op_sel_hi:[1,1,0] neg_lo:[0,0,1] neg_hi:[0,0,1]
	s_nop 0
	v_pk_fma_f32 v[108:109], v[38:39], v[38:39], v[106:107]
	v_mov_b32_e32 v106, v40
	v_mov_b32_e32 v107, v110
	v_mul_f32_e32 v40, v163, v110
	v_pk_fma_f32 v[106:107], v[162:163], v[106:107], v[40:41] op_sel_hi:[1,1,0] neg_lo:[0,0,1] neg_hi:[0,0,1]
	v_mov_b32_e32 v110, v41
	v_mul_f32_e32 v40, v163, v111
	v_pk_fma_f32 v[108:109], v[106:107], v[106:107], v[108:109]
	v_pk_fma_f32 v[40:41], v[162:163], v[110:111], v[40:41] op_sel_hi:[1,1,0] neg_lo:[0,0,1] neg_hi:[0,0,1]
	s_nop 0
	v_pk_fma_f32 v[110:111], v[40:41], v[40:41], v[108:109]
	v_mov_b32_e32 v108, v42
	v_mov_b32_e32 v109, v112
	v_mul_f32_e32 v42, v163, v112
	v_pk_fma_f32 v[108:109], v[162:163], v[108:109], v[42:43] op_sel_hi:[1,1,0] neg_lo:[0,0,1] neg_hi:[0,0,1]
	v_mov_b32_e32 v112, v43
	v_mul_f32_e32 v42, v163, v113
	v_pk_fma_f32 v[110:111], v[108:109], v[108:109], v[110:111]
	v_pk_fma_f32 v[42:43], v[162:163], v[112:113], v[42:43] op_sel_hi:[1,1,0] neg_lo:[0,0,1] neg_hi:[0,0,1]
	s_nop 0
	v_pk_fma_f32 v[112:113], v[42:43], v[42:43], v[110:111]
	v_mov_b32_e32 v110, v44
	v_mov_b32_e32 v111, v114
	v_mul_f32_e32 v44, v163, v114
	v_pk_fma_f32 v[110:111], v[162:163], v[110:111], v[44:45] op_sel_hi:[1,1,0] neg_lo:[0,0,1] neg_hi:[0,0,1]
	v_mov_b32_e32 v114, v45
	v_mul_f32_e32 v44, v163, v115
	v_pk_fma_f32 v[112:113], v[110:111], v[110:111], v[112:113]
	v_pk_fma_f32 v[44:45], v[162:163], v[114:115], v[44:45] op_sel_hi:[1,1,0] neg_lo:[0,0,1] neg_hi:[0,0,1]
	s_nop 0
	v_pk_fma_f32 v[114:115], v[44:45], v[44:45], v[112:113]
	v_mov_b32_e32 v112, v46
	v_mov_b32_e32 v113, v116
	v_mul_f32_e32 v46, v163, v116
	v_pk_fma_f32 v[112:113], v[162:163], v[112:113], v[46:47] op_sel_hi:[1,1,0] neg_lo:[0,0,1] neg_hi:[0,0,1]
	v_mov_b32_e32 v116, v47
	v_mul_f32_e32 v46, v163, v117
	v_pk_fma_f32 v[114:115], v[112:113], v[112:113], v[114:115]
	v_pk_fma_f32 v[46:47], v[162:163], v[116:117], v[46:47] op_sel_hi:[1,1,0] neg_lo:[0,0,1] neg_hi:[0,0,1]
	s_nop 0
	v_pk_fma_f32 v[116:117], v[46:47], v[46:47], v[114:115]
	v_mov_b32_e32 v114, v48
	v_mov_b32_e32 v115, v118
	v_mul_f32_e32 v48, v163, v118
	v_pk_fma_f32 v[114:115], v[162:163], v[114:115], v[48:49] op_sel_hi:[1,1,0] neg_lo:[0,0,1] neg_hi:[0,0,1]
	v_mov_b32_e32 v118, v49
	v_mul_f32_e32 v48, v163, v119
	v_pk_fma_f32 v[116:117], v[114:115], v[114:115], v[116:117]
	v_pk_fma_f32 v[48:49], v[162:163], v[118:119], v[48:49] op_sel_hi:[1,1,0] neg_lo:[0,0,1] neg_hi:[0,0,1]
	s_nop 0
	v_pk_fma_f32 v[118:119], v[48:49], v[48:49], v[116:117]
	v_mov_b32_e32 v116, v18
	v_mov_b32_e32 v117, v120
	v_mul_f32_e32 v18, v163, v120
	v_pk_fma_f32 v[116:117], v[162:163], v[116:117], v[18:19] op_sel_hi:[1,1,0] neg_lo:[0,0,1] neg_hi:[0,0,1]
	v_mov_b32_e32 v120, v19
	v_mul_f32_e32 v18, v163, v121
	v_pk_fma_f32 v[118:119], v[116:117], v[116:117], v[118:119]
	v_pk_fma_f32 v[18:19], v[162:163], v[120:121], v[18:19] op_sel_hi:[1,1,0] neg_lo:[0,0,1] neg_hi:[0,0,1]
	s_nop 0
	v_pk_fma_f32 v[120:121], v[18:19], v[18:19], v[118:119]
	v_mov_b32_e32 v118, v20
	v_mov_b32_e32 v119, v122
	v_mul_f32_e32 v20, v163, v122
	v_pk_fma_f32 v[118:119], v[162:163], v[118:119], v[20:21] op_sel_hi:[1,1,0] neg_lo:[0,0,1] neg_hi:[0,0,1]
	v_mov_b32_e32 v122, v21
	v_mul_f32_e32 v20, v163, v123
	v_pk_fma_f32 v[120:121], v[118:119], v[118:119], v[120:121]
	v_pk_fma_f32 v[20:21], v[162:163], v[122:123], v[20:21] op_sel_hi:[1,1,0] neg_lo:[0,0,1] neg_hi:[0,0,1]
	s_nop 0
	v_pk_fma_f32 v[122:123], v[20:21], v[20:21], v[120:121]
	v_mov_b32_e32 v120, v22
	v_mov_b32_e32 v121, v124
	v_mul_f32_e32 v22, v163, v124
	v_pk_fma_f32 v[120:121], v[162:163], v[120:121], v[22:23] op_sel_hi:[1,1,0] neg_lo:[0,0,1] neg_hi:[0,0,1]
	v_mov_b32_e32 v124, v23
	v_mul_f32_e32 v22, v163, v125
	v_pk_fma_f32 v[122:123], v[120:121], v[120:121], v[122:123]
	v_pk_fma_f32 v[22:23], v[162:163], v[124:125], v[22:23] op_sel_hi:[1,1,0] neg_lo:[0,0,1] neg_hi:[0,0,1]
	s_nop 0
	v_pk_fma_f32 v[124:125], v[22:23], v[22:23], v[122:123]
	v_mov_b32_e32 v122, v24
	v_mov_b32_e32 v123, v126
	v_mul_f32_e32 v24, v163, v126
	v_pk_fma_f32 v[122:123], v[162:163], v[122:123], v[24:25] op_sel_hi:[1,1,0] neg_lo:[0,0,1] neg_hi:[0,0,1]
	v_mov_b32_e32 v126, v25
	v_mul_f32_e32 v24, v163, v127
	v_pk_fma_f32 v[124:125], v[122:123], v[122:123], v[124:125]
	v_pk_fma_f32 v[24:25], v[162:163], v[126:127], v[24:25] op_sel_hi:[1,1,0] neg_lo:[0,0,1] neg_hi:[0,0,1]
	s_nop 0
	v_pk_fma_f32 v[126:127], v[24:25], v[24:25], v[124:125]
	v_mov_b32_e32 v124, v26
	s_waitcnt lgkmcnt(2)
	v_mov_b32_e32 v125, v128
	v_mul_f32_e32 v26, v163, v128
	v_pk_fma_f32 v[124:125], v[162:163], v[124:125], v[26:27] op_sel_hi:[1,1,0] neg_lo:[0,0,1] neg_hi:[0,0,1]
	v_mov_b32_e32 v128, v27
	v_mul_f32_e32 v26, v163, v129
	v_pk_fma_f32 v[126:127], v[124:125], v[124:125], v[126:127]
	v_pk_fma_f32 v[26:27], v[162:163], v[128:129], v[26:27] op_sel_hi:[1,1,0] neg_lo:[0,0,1] neg_hi:[0,0,1]
	s_nop 0
	v_pk_fma_f32 v[128:129], v[26:27], v[26:27], v[126:127]
	v_mov_b32_e32 v126, v28
	s_waitcnt lgkmcnt(1)
	v_mov_b32_e32 v127, v130
	v_mul_f32_e32 v28, v163, v130
	v_pk_fma_f32 v[126:127], v[162:163], v[126:127], v[28:29] op_sel_hi:[1,1,0] neg_lo:[0,0,1] neg_hi:[0,0,1]
	v_mov_b32_e32 v130, v29
	v_mul_f32_e32 v28, v163, v131
	v_pk_fma_f32 v[128:129], v[126:127], v[126:127], v[128:129]
	v_pk_fma_f32 v[28:29], v[162:163], v[130:131], v[28:29] op_sel_hi:[1,1,0] neg_lo:[0,0,1] neg_hi:[0,0,1]
	s_nop 0
	v_pk_fma_f32 v[130:131], v[28:29], v[28:29], v[128:129]
	v_mov_b32_e32 v128, v30
	s_waitcnt lgkmcnt(0)
; __device__ __forceinline__ unsigned cvtpk(float lo, float hi) { unsigned r; asm volatile("v_cvt_pk_bf16_f32 %0, %1, %2" : "=v"(r) : "v"(lo), "v"(hi)); return r; }
; __device__ __forceinline__ void attnB_unit(const bf16* Q, const bf16* __restrict__ K, const bf16* __restrict__ V, bf16* O, long rowbase, int seq, int h, int q0, float lam, char* lds, LAS unsigned char* lds3) {
;     ...
;             for (int r = 0; r < 16; ++r) { const float v = o[d0][r] * rl - lam * X[(d0 * 16 + r) * 64]; o[d0][r] = v; ss += v * v; }
;         { auto rr = __builtin_amdgcn_permlane32_swap(__float_as_uint(ss), __float_as_uint(ss), false, false); ss = __uint_as_float(rr[0]) + __uint_as_float(rr[1]); }
;         const float rs = __builtin_amdgcn_rsqf(ss * (1.f / 128.f) + RMS_EPS);
;         bf16* Ow = O + (size_t)(rowbase + q0 + wq * 32 + r32) * DM + h * 128 + 4 * hi;
; #pragma unroll
;         for (int d0 = 0; d0 < 4; ++d0)
; #pragma unroll
;             for (int g4 = 0; g4 < 4; ++g4) { u32x2 w; w.x = cvtpk(o[d0][4 * g4] * rs, o[d0][4 * g4 + 1] * rs); w.y = cvtpk(o[d0][4 * g4 + 2] * rs, o[d0][4 * g4 + 3] * rs);
;                 *(u32x2*)(Ow + d0 * 32 + 8 * g4) = w; }
	v_mov_b32_e32 v129, v132
	v_mul_f32_e32 v30, v163, v132
	v_pk_fma_f32 v[128:129], v[162:163], v[128:129], v[30:31] op_sel_hi:[1,1,0] neg_lo:[0,0,1] neg_hi:[0,0,1]
	v_mov_b32_e32 v132, v31
	v_mul_f32_e32 v30, v163, v133
	v_pk_fma_f32 v[30:31], v[162:163], v[132:133], v[30:31] op_sel_hi:[1,1,0] neg_lo:[0,0,1] neg_hi:[0,0,1]
	ds_read2st64_b32 v[132:133], v1 offset0:62 offset1:63
	v_pk_fma_f32 v[130:131], v[128:129], v[128:129], v[130:131]
	s_waitcnt lgkmcnt(0)
	v_pk_mul_f32 v[132:133], v[164:165], v[132:133]
	v_pk_fma_f32 v[130:131], v[30:31], v[30:31], v[130:131]
	v_pk_fma_f32 v[32:33], v[162:163], v[32:33], v[132:133] op_sel_hi:[0,1,1] neg_lo:[0,0,1] neg_hi:[0,0,1]
	v_pk_fma_f32 v[130:131], v[32:33], v[32:33], v[130:131]
	v_mul_f32_e32 v132, v33, v33
	v_pk_add_f32 v[130:131], v[130:131], v[132:133] op_sel_hi:[1,0]
	s_nop 0
	v_mov_b32_e32 v1, v130
	s_nop 1
	v_permlane32_swap_b32_e32 v130, v1
	v_add_f32_e32 v1, v130, v1
	v_fmamk_f32 v1, v1, 0x3c000000, v201
	v_rsq_f32_e32 v1, v1
	v_lshlrev_b32_e32 v130, 3, v17
	v_mov_b32_e32 v131, v0
	v_lshl_add_u64 v[130:131], v[166:167], 0, v[130:131]
	v_and_b32_e32 v247, 31, v188
	v_lshlrev_b32_e32 v247, 8, v247
	v_lshrrev_b32_e32 v248, 5, v188
	v_xor_b32_e32 v248, v248, v188
	v_and_b32_e32 v248, 1, v248
	v_and_b32_e32 v249, 14, v188
	v_or_b32_e32 v248, v248, v249
	v_lshl_or_b32 v247, v248, 4, v247
	v_mov_b32_e32 v249, s29
	v_lshlrev_b32_e32 v249, 13, v249
	v_add_u32_e32 v249, 0x10000, v249
	v_add_u32_e32 v247, v247, v249
	v_lshrrev_b32_e32 v250, 4, v188
	v_and_b32_e32 v251, 15, v188
	v_xor_b32_e32 v251, v251, v250
	v_lshlrev_b32_e32 v250, 8, v250
	v_lshl_or_b32 v250, v251, 4, v250
	v_add_u32_e32 v250, v250, v249
	v_lshrrev_b32_e32 v251, 4, v188
	v_and_b32_e32 v252, 31, v188
	v_sub_u32_e32 v251, v251, v252
	v_lshlrev_b32_e32 v251, 11, v251
	v_and_b32_e32 v252, 15, v188
	v_lshl_add_u32 v252, v252, 4, v251
	v_ashrrev_i32_e32 v253, 31, v252
	v_lshl_add_u64 v[252:253], v[166:167], 0, v[252:253]
	v_mul_f32_e32 v236, v2, v1
	v_mul_f32_e32 v246, v4, v1
	v_cvt_pk_bf16_f32 v236, v236, v246
	v_mul_f32_e32 v237, v6, v1
	v_mul_f32_e32 v246, v8, v1
	v_cvt_pk_bf16_f32 v237, v237, v246
	v_mul_f32_e32 v238, v10, v1
	v_mul_f32_e32 v246, v12, v1
	v_cvt_pk_bf16_f32 v238, v238, v246
	v_mul_f32_e32 v239, v14, v1
	v_mul_f32_e32 v246, v66, v1
	v_cvt_pk_bf16_f32 v239, v239, v246
	v_xor_b32_e32 v254, 0x0, v247
	s_nop 0
	v_permlane32_swap_b32_e32 v236, v238
	v_permlane32_swap_b32_e32 v237, v239
	ds_write_b128 v254, v[236:239]
	v_mul_f32_e32 v240, v68, v1
	v_mul_f32_e32 v246, v70, v1
	v_cvt_pk_bf16_f32 v240, v240, v246
	v_mul_f32_e32 v241, v72, v1
	v_mul_f32_e32 v246, v74, v1
	v_cvt_pk_bf16_f32 v241, v241, v246
	v_mul_f32_e32 v242, v76, v1
	v_mul_f32_e32 v246, v78, v1
	v_cvt_pk_bf16_f32 v242, v242, v246
	v_mul_f32_e32 v243, v82, v1
	v_mul_f32_e32 v246, v80, v1
	v_cvt_pk_bf16_f32 v243, v243, v246
	v_xor_b32_e32 v254, 0x20, v247
	s_nop 0
	v_permlane32_swap_b32_e32 v240, v242
	v_permlane32_swap_b32_e32 v241, v243
	ds_write_b128 v254, v[240:243]
	v_mul_f32_e32 v236, v84, v1
	v_mul_f32_e32 v246, v50, v1
	v_cvt_pk_bf16_f32 v236, v236, v246
	v_mul_f32_e32 v237, v86, v1
	v_mul_f32_e32 v246, v52, v1
	v_cvt_pk_bf16_f32 v237, v237, v246
	v_mul_f32_e32 v238, v88, v1
	v_mul_f32_e32 v246, v54, v1
	v_cvt_pk_bf16_f32 v238, v238, v246
	v_mul_f32_e32 v239, v90, v1
	v_mul_f32_e32 v246, v56, v1
	v_cvt_pk_bf16_f32 v239, v239, v246
	v_xor_b32_e32 v254, 0x40, v247
	s_nop 0
	v_permlane32_swap_b32_e32 v236, v238
	v_permlane32_swap_b32_e32 v237, v239
	ds_write_b128 v254, v[236:239]
	v_mul_f32_e32 v240, v92, v1
	v_mul_f32_e32 v246, v58, v1
	v_cvt_pk_bf16_f32 v240, v240, v246
	v_mul_f32_e32 v241, v94, v1
	v_mul_f32_e32 v246, v60, v1
	v_cvt_pk_bf16_f32 v241, v241, v246
	v_mul_f32_e32 v242, v96, v1
	v_mul_f32_e32 v246, v62, v1
	v_cvt_pk_bf16_f32 v242, v242, v246
	v_mul_f32_e32 v243, v98, v1
	v_mul_f32_e32 v246, v64, v1
	v_cvt_pk_bf16_f32 v243, v243, v246
	v_xor_b32_e32 v254, 0x60, v247
	s_nop 0
	v_permlane32_swap_b32_e32 v240, v242
	v_permlane32_swap_b32_e32 v241, v243
	ds_write_b128 v254, v[240:243]
	v_mul_f32_e32 v236, v100, v1
	v_mul_f32_e32 v246, v34, v1
	v_cvt_pk_bf16_f32 v236, v236, v246
	v_mul_f32_e32 v237, v102, v1
	v_mul_f32_e32 v246, v36, v1
	v_cvt_pk_bf16_f32 v237, v237, v246
	v_mul_f32_e32 v238, v104, v1
	v_mul_f32_e32 v246, v38, v1
	v_cvt_pk_bf16_f32 v238, v238, v246
	v_mul_f32_e32 v239, v106, v1
	v_mul_f32_e32 v246, v40, v1
	v_cvt_pk_bf16_f32 v239, v239, v246
	v_xor_b32_e32 v254, 0x80, v247
	s_nop 0
	v_permlane32_swap_b32_e32 v236, v238
	v_permlane32_swap_b32_e32 v237, v239
	ds_write_b128 v254, v[236:239]
	v_mul_f32_e32 v240, v108, v1
	v_mul_f32_e32 v246, v42, v1
	v_cvt_pk_bf16_f32 v240, v240, v246
	v_mul_f32_e32 v241, v110, v1
	v_mul_f32_e32 v246, v44, v1
	v_cvt_pk_bf16_f32 v241, v241, v246
	v_mul_f32_e32 v242, v112, v1
	v_mul_f32_e32 v246, v46, v1
	v_cvt_pk_bf16_f32 v242, v242, v246
	v_mul_f32_e32 v243, v114, v1
	v_mul_f32_e32 v246, v48, v1
	v_cvt_pk_bf16_f32 v243, v243, v246
	v_xor_b32_e32 v254, 0xa0, v247
	s_nop 0
	v_permlane32_swap_b32_e32 v240, v242
	v_permlane32_swap_b32_e32 v241, v243
	ds_write_b128 v254, v[240:243]
	v_mul_f32_e32 v236, v116, v1
	v_mul_f32_e32 v246, v18, v1
	v_cvt_pk_bf16_f32 v236, v236, v246
	v_mul_f32_e32 v237, v118, v1
	v_mul_f32_e32 v246, v20, v1
	v_cvt_pk_bf16_f32 v237, v237, v246
	v_mul_f32_e32 v238, v120, v1
	v_mul_f32_e32 v246, v22, v1
	v_cvt_pk_bf16_f32 v238, v238, v246
	v_mul_f32_e32 v239, v122, v1
	v_mul_f32_e32 v246, v24, v1
	v_cvt_pk_bf16_f32 v239, v239, v246
	v_xor_b32_e32 v254, 0xc0, v247
	s_nop 0
	v_permlane32_swap_b32_e32 v236, v238
	v_permlane32_swap_b32_e32 v237, v239
	ds_write_b128 v254, v[236:239]
	v_mul_f32_e32 v240, v124, v1
	v_mul_f32_e32 v246, v26, v1
	v_cvt_pk_bf16_f32 v240, v240, v246
	v_mul_f32_e32 v241, v126, v1
	v_mul_f32_e32 v246, v28, v1
	v_cvt_pk_bf16_f32 v241, v241, v246
	v_mul_f32_e32 v242, v128, v1
	v_mul_f32_e32 v246, v30, v1
	v_cvt_pk_bf16_f32 v242, v242, v246
	v_mul_f32_e32 v243, v32, v1
	v_mul_f32_e32 v246, v33, v1
	v_cvt_pk_bf16_f32 v243, v243, v246
	v_xor_b32_e32 v254, 0xe0, v247
	s_nop 0
	v_permlane32_swap_b32_e32 v240, v242
	v_permlane32_swap_b32_e32 v241, v243
	ds_write_b128 v254, v[240:243]
	s_waitcnt lgkmcnt(0)
; __device__ __forceinline__ unsigned cvtpk(float lo, float hi) { unsigned r; asm volatile("v_cvt_pk_bf16_f32 %0, %1, %2" : "=v"(r) : "v"(lo), "v"(hi)); return r; }
; __device__ __forceinline__ void attnB_unit(const bf16* Q, const bf16* __restrict__ K, const bf16* __restrict__ V, bf16* O, long rowbase, int seq, int h, int q0, float lam, char* lds, LAS unsigned char* lds3) {
;     ...
;         bf16* Ow = O + (size_t)(rowbase + q0 + wq * 32 + r32) * DM + h * 128 + 4 * hi;
; #pragma unroll
;         for (int d0 = 0; d0 < 4; ++d0)
; #pragma unroll
;             for (int g4 = 0; g4 < 4; ++g4) { u32x2 w; w.x = cvtpk(o[d0][4 * g4] * rs, o[d0][4 * g4 + 1] * rs); w.y = cvtpk(o[d0][4 * g4 + 2] * rs, o[d0][4 * g4 + 3] * rs);
;                 *(u32x2*)(Ow + d0 * 32 + 8 * g4) = w; }
	v_xor_b32_e32 v254, 0x0, v250
	ds_read_b128 v[236:239], v254
	v_xor_b32_e32 v254, 0x40, v250
	ds_read_b128 v[240:243], v254 offset:1024
	s_waitcnt lgkmcnt(1)
	global_store_dwordx4 v[252:253], v[236:239], off
	v_add_co_u32_e32 v252, vcc, 0x2000, v252
	v_addc_co_u32_e32 v253, vcc, 0, v253, vcc
	v_xor_b32_e32 v254, 0x80, v250
	ds_read_b128 v[236:239], v254 offset:2048
	s_waitcnt lgkmcnt(1)
	global_store_dwordx4 v[252:253], v[240:243], off
	v_add_co_u32_e32 v252, vcc, 0x2000, v252
	v_addc_co_u32_e32 v253, vcc, 0, v253, vcc
	v_xor_b32_e32 v254, 0xc0, v250
	ds_read_b128 v[240:243], v254 offset:3072
	s_waitcnt lgkmcnt(1)
	global_store_dwordx4 v[252:253], v[236:239], off
	v_add_co_u32_e32 v252, vcc, 0x2000, v252
	v_addc_co_u32_e32 v253, vcc, 0, v253, vcc
	v_xor_b32_e32 v254, 0x0, v250
	ds_read_b128 v[236:239], v254 offset:4096
	s_waitcnt lgkmcnt(1)
	global_store_dwordx4 v[252:253], v[240:243], off
	v_add_co_u32_e32 v252, vcc, 0x2000, v252
	v_addc_co_u32_e32 v253, vcc, 0, v253, vcc
	v_xor_b32_e32 v254, 0x40, v250
	ds_read_b128 v[240:243], v254 offset:5120
	s_waitcnt lgkmcnt(1)
	global_store_dwordx4 v[252:253], v[236:239], off
	v_add_co_u32_e32 v252, vcc, 0x2000, v252
	v_addc_co_u32_e32 v253, vcc, 0, v253, vcc
	v_xor_b32_e32 v254, 0x80, v250
	ds_read_b128 v[236:239], v254 offset:6144
	s_waitcnt lgkmcnt(1)
	global_store_dwordx4 v[252:253], v[240:243], off
	v_add_co_u32_e32 v252, vcc, 0x2000, v252
	v_addc_co_u32_e32 v253, vcc, 0, v253, vcc
	v_xor_b32_e32 v254, 0xc0, v250
	ds_read_b128 v[240:243], v254 offset:7168
	s_waitcnt lgkmcnt(1)
	global_store_dwordx4 v[252:253], v[236:239], off
	v_add_co_u32_e32 v252, vcc, 0x2000, v252
	v_addc_co_u32_e32 v253, vcc, 0, v253, vcc
	s_waitcnt lgkmcnt(0)
	global_store_dwordx4 v[252:253], v[240:243], off
	s_branch .LBB0_265
